# XCD grid barrier: first arriver of each XCD starts an early L2 write-back
# baseline (speedup 1.0000x reference)
.LBB0_1181:
	s_or_b64 exec, exec, s[2:3]
	v_cvt_f32_u32_e32 v5, v3
	s_waitcnt vmcnt(0)
	v_readfirstlane_b32 s2, v4
	v_sub_u32_e32 v4, 0, v3
	v_rcp_iflag_f32_e32 v5, v5
	v_add_u32_e32 v6, s2, v0
	v_mul_f32_e32 v5, 0x4f7ffffe, v5
	v_cvt_u32_f32_e32 v5, v5
	v_mul_lo_u32 v0, v4, v5
	v_mul_hi_u32 v0, v5, v0
	v_add_u32_e32 v0, v5, v0
	v_mul_hi_u32 v0, v6, v0
	v_mul_lo_u32 v4, v0, v3
	v_sub_u32_e32 v4, v6, v4
	v_add_u32_e32 v5, 1, v0
	v_cmp_ge_u32_e32 vcc, v4, v3
	s_nop 1
	v_cndmask_b32_e32 v0, v0, v5, vcc
	v_sub_u32_e32 v5, v4, v3
	v_cndmask_b32_e32 v4, v4, v5, vcc
	v_add_u32_e32 v5, 1, v0
	v_cmp_ge_u32_e32 vcc, v4, v3
	v_add_u32_e32 v4, 1, v6
	s_nop 0
	v_cndmask_b32_e32 v0, v0, v5, vcc
	v_mul_lo_u32 v5, v3, v0
	v_cmp_eq_u32_e32 vcc, v6, v5
	s_cbranch_vccz .Lgb_nofirst
	buffer_wbl2 sc1
.Lgb_nofirst:
	v_add_u32_e32 v3, v5, v3
	v_cmp_ne_u32_e32 vcc, v4, v3
	s_and_saveexec_b64 s[2:3], vcc
	s_xor_b64 s[2:3], exec, s[2:3]
	s_cbranch_execz .LBB0_1195
	v_readlane_b32 s4, v252, 9
	v_readlane_b32 s5, v252, 10
	s_waitcnt lgkmcnt(0)
	s_nop 3
	global_load_dword v2, v1, s[4:5] sc1
	s_waitcnt vmcnt(0)
	v_cmp_eq_u32_e32 vcc, v2, v0
	s_and_saveexec_b64 s[4:5], vcc
	s_cbranch_execz .LBB0_1194
	s_mov_b32 s16, 1
	s_mov_b64 s[6:7], 0
	s_branch .LBB0_1185
